# attention PV first key-half: all 8 V fragments prefetched up front (address math hoisted), MFMA pairs back-to-back behind counted lgkmcnt
# baseline (speedup 1.0000x reference)
.Lmy_at_s1:
	v_exp_f32_e32 v170, v116
	v_fma_f32 v116, v178, s27, -v160
	v_add3_u32 v139, s10, v115, v114
	v_add3_u32 v190, s10, v152, v114
	v_add3_u32 v191, s10, v153, v114
	v_add3_u32 v192, s10, v154, v114
	v_add_u32_e32 v173, 0x4000, v139
	v_add_u32_e32 v190, 0x4000, v190
	v_add_u32_e32 v191, 0x4000, v191
	v_add_u32_e32 v192, 0x4000, v192
	v_add_u32_e32 v193, 0x6800, v139
	v_add_u32_e32 v194, 0x7000, v139
	v_add_u32_e32 v195, 0x7800, v139
	v_add_u32_e32 v139, 0x8000, v139
	v_fma_f32 v128, v182, s27, -v160
	v_fma_f32 v130, v183, s27, -v160
	v_fma_f32 v132, v184, s27, -v160
	v_fma_f32 v134, v185, s27, -v160
	ds_read_b64 v[174:175], v173 offset:1024
	ds_read_b64 v[176:177], v173 offset:1056
	ds_read_b64 v[182:183], v190 offset:1024
	ds_read_b64 v[184:185], v190 offset:1056
	ds_read_b64 v[230:231], v191 offset:1024
	ds_read_b64 v[232:233], v191 offset:1056
	ds_read_b64 v[234:235], v192 offset:1024
	ds_read_b64 v[236:237], v192 offset:1056
	ds_read_b64 v[238:239], v193
	ds_read_b64 v[240:241], v193 offset:32
	ds_read_b64 v[242:243], v194 offset:256
	ds_read_b64 v[244:245], v194 offset:288
	ds_read_b64 v[246:247], v195 offset:512
	ds_read_b64 v[248:249], v195 offset:544
	ds_read_b64 v[250:251], v139 offset:768
	ds_read_b64 v[252:253], v139 offset:800
	v_exp_f32_e32 v171, v116
	v_fma_f32 v116, v179, s27, -v160
	v_exp_f32_e32 v172, v116
	v_fma_f32 v116, v180, s27, -v160
	v_fma_f32 v118, v181, s27, -v160
	v_exp_f32_e32 v116, v116
	v_exp_f32_e32 v118, v118
	v_cvt_pk_bf16_f32 v143, v117, v119
	v_cvt_pk_bf16_f32 v142, v165, v166
	v_cvt_pk_bf16_f32 v141, v163, v164
	v_cvt_pk_bf16_f32 v140, v161, v162
	v_cvt_pk_bf16_f32 v181, v116, v118
	v_cvt_pk_bf16_f32 v180, v171, v172
	v_cvt_pk_bf16_f32 v179, v169, v170
	v_cvt_pk_bf16_f32 v178, v167, v168
	s_waitcnt lgkmcnt(14)
	v_mfma_f32_16x16x32_bf16 v[96:99], v[174:177], v[140:143], v[96:99]
	v_mfma_f32_16x16x32_bf16 v[80:83], v[174:177], v[178:181], v[80:83]
	s_waitcnt lgkmcnt(12)
	v_mfma_f32_16x16x32_bf16 v[92:95], v[182:185], v[140:143], v[92:95]
	v_mfma_f32_16x16x32_bf16 v[68:71], v[182:185], v[178:181], v[68:71]
	s_waitcnt lgkmcnt(10)
	v_mfma_f32_16x16x32_bf16 v[76:79], v[230:233], v[140:143], v[76:79]
	v_mfma_f32_16x16x32_bf16 v[56:59], v[230:233], v[178:181], v[56:59]
	s_waitcnt lgkmcnt(8)
	v_mfma_f32_16x16x32_bf16 v[72:75], v[234:237], v[140:143], v[72:75]
	v_mfma_f32_16x16x32_bf16 v[24:27], v[234:237], v[178:181], v[24:27]
	s_waitcnt lgkmcnt(6)
	v_mfma_f32_16x16x32_bf16 v[60:63], v[238:241], v[140:143], v[60:63]
	v_mfma_f32_16x16x32_bf16 v[64:67], v[238:241], v[178:181], v[64:67]
	v_fma_f32 v120, v186, s27, -v160
	s_waitcnt lgkmcnt(4)
	v_mfma_f32_16x16x32_bf16 v[28:31], v[242:245], v[140:143], v[28:31]
	v_fma_f32 v122, v187, s27, -v160
	v_fma_f32 v124, v188, s27, -v160
	v_fma_f32 v126, v189, s27, -v160
	v_mfma_f32_16x16x32_bf16 v[44:47], v[242:245], v[178:181], v[44:47]
	ds_read_b64 v[196:197], v190 offset:1088
	ds_read_b64 v[198:199], v190 offset:1120
	ds_read_b64 v[200:201], v173 offset:1088
	ds_read_b64 v[202:203], v173 offset:1120
	ds_read_b64 v[204:205], v191 offset:1088
	ds_read_b64 v[206:207], v191 offset:1120
	ds_read_b64 v[208:209], v192 offset:1088
	ds_read_b64 v[210:211], v192 offset:1120
	ds_read_b64 v[212:213], v193 offset:64
	ds_read_b64 v[214:215], v193 offset:96
	ds_read_b64 v[216:217], v194 offset:320
	ds_read_b64 v[218:219], v194 offset:352
	ds_read_b64 v[220:221], v195 offset:576
	ds_read_b64 v[222:223], v195 offset:608
	ds_read_b64 v[226:227], v139 offset:832
	ds_read_b64 v[228:229], v139 offset:864
	v_exp_f32_e32 v120, v120
	v_exp_f32_e32 v122, v122
	s_waitcnt lgkmcnt(15)
	v_mfma_f32_16x16x32_bf16 v[32:35], v[246:249], v[178:181], v[32:35]
	v_exp_f32_e32 v124, v124
	v_exp_f32_e32 v126, v126
	v_exp_f32_e32 v128, v128
	s_waitcnt lgkmcnt(15)
	v_mfma_f32_16x16x32_bf16 v[88:91], v[250:253], v[178:181], v[88:91]
	v_exp_f32_e32 v130, v130
	v_exp_f32_e32 v132, v132
	v_exp_f32_e32 v134, v134
	v_mfma_f32_16x16x32_bf16 v[20:23], v[246:249], v[140:143], v[20:23]
	v_cvt_pk_bf16_f32 v177, v133, v135
	v_cvt_pk_bf16_f32 v176, v129, v131
	v_cvt_pk_bf16_f32 v175, v125, v127
	v_mfma_f32_16x16x32_bf16 v[84:87], v[250:253], v[140:143], v[84:87]
	v_cvt_pk_bf16_f32 v174, v121, v123
	v_cvt_pk_bf16_f32 v143, v132, v134
	v_cvt_pk_bf16_f32 v142, v128, v130
	v_cvt_pk_bf16_f32 v141, v124, v126
	v_cvt_pk_bf16_f32 v140, v120, v122
	s_waitcnt lgkmcnt(14)
	v_mfma_f32_16x16x32_bf16 v[92:95], v[196:199], v[174:177], v[92:95]
	v_mfma_f32_16x16x32_bf16 v[68:71], v[196:199], v[140:143], v[68:71]
	s_waitcnt lgkmcnt(10)
	v_mfma_f32_16x16x32_bf16 v[76:79], v[204:207], v[174:177], v[76:79]
	v_mfma_f32_16x16x32_bf16 v[56:59], v[204:207], v[140:143], v[56:59]
	s_waitcnt lgkmcnt(8)
	v_mfma_f32_16x16x32_bf16 v[72:75], v[208:211], v[174:177], v[72:75]
	v_mfma_f32_16x16x32_bf16 v[24:27], v[208:211], v[140:143], v[24:27]
	s_waitcnt lgkmcnt(6)
	v_mfma_f32_16x16x32_bf16 v[60:63], v[212:215], v[174:177], v[60:63]
	v_mfma_f32_16x16x32_bf16 v[64:67], v[212:215], v[140:143], v[64:67]
	s_waitcnt lgkmcnt(4)
	v_mfma_f32_16x16x32_bf16 v[28:31], v[216:219], v[174:177], v[28:31]
	v_mfma_f32_16x16x32_bf16 v[44:47], v[216:219], v[140:143], v[44:47]
	s_waitcnt lgkmcnt(2)
	v_mfma_f32_16x16x32_bf16 v[20:23], v[220:223], v[174:177], v[20:23]
	v_mfma_f32_16x16x32_bf16 v[32:35], v[220:223], v[140:143], v[32:35]
	v_mfma_f32_16x16x32_bf16 v[96:99], v[200:203], v[174:177], v[96:99]
	v_mfma_f32_16x16x32_bf16 v[80:83], v[200:203], v[140:143], v[80:83]
	s_waitcnt lgkmcnt(0)
	v_mfma_f32_16x16x32_bf16 v[84:87], v[226:229], v[174:177], v[84:87]
	v_mfma_f32_16x16x32_bf16 v[88:91], v[226:229], v[140:143], v[88:91]
	s_and_saveexec_b64 s[10:11], s[6:7]
	s_cbranch_execz .LBB0_717
	s_cmp_eq_u32 s13, 1
	s_cselect_b32 s6, 0x8c00, 0
	s_add_i32 s6, s6, 16
	v_add3_u32 v139, s6, v155, v102
	s_waitcnt vmcnt(0)
	ds_write_b128 v139, v[4:7]
	ds_write_b128 v139, v[8:11] offset:8704
	v_add3_u32 v139, s6, v156, v104
	ds_write_b128 v139, v[12:15] offset:17408
	ds_write_b128 v139, v[16:19] offset:26624
	s_branch .LBB0_717
